# v19 + hyena shifted-copy build fast path: when the 1168-tap window is wholly inside the filter buffer (wave-uniform test) the 19 per-element range checks and exec masks are skipped (one base address,
# speedup vs baseline: 1.0031x; 1.0028x over previous
; __device__ __forceinline__ void hyena_item(const Ctx& C, ArgsP a, int ly, int c, bf16_t* yout) {
;     ...
;             const int xs = 8192 - 128 * dhi - 128;
;             { bf16_t* dst = Wb + wave * WW; const int x0 = xs - wave;
;               bf16_t tv[19];
; #pragma unroll
;               for (int it = 0; it < 19; ++it) { const int yy = lane + 64 * it; const int xi = x0 + yy; tv[it] = (yy < WW && xi >= 0 && xi < 16384) ? R[xi] : (bf16_t)0; }
; #pragma unroll
;               for (int it = 0; it < 19; ++it) { const int yy = lane + 64 * it; if (yy < WW) dst[yy] = tv[it]; } }
;             __syncthreads();
.LBB0_812:
	s_lshl_b32 s6, s72, 10
	s_add_i32 s6, s6, s1
	s_sub_i32 s73, 0x3c00, s6
	s_cmp_lt_u32 s73, 0x3b70
	s_cbranch_scc1 .Lhy_wfast
	s_waitcnt lgkmcnt(3)
	v_add_u32_e32 v67, s73, v109
	v_cmp_gt_u32_e32 vcc, s52, v67
	v_mov_b32_e32 v1, 0
	v_mov_b32_e32 v66, 0
	s_and_saveexec_b64 s[56:57], vcc
	v_lshl_add_u32 v66, v67, 1, 0
	v_add_u32_e32 v66, 0x12000, v66
	ds_read_u16 v66, v66
	s_or_b64 exec, exec, s[56:57]
	v_add_u32_e32 v67, s73, v185
	v_cmp_gt_u32_e32 vcc, s52, v67
	s_and_saveexec_b64 s[56:57], vcc
	v_lshl_add_u32 v1, v67, 1, 0
	v_add_u32_e32 v1, 0x12000, v1
	ds_read_u16 v1, v1
	s_or_b64 exec, exec, s[56:57]
	v_add_u32_e32 v69, s73, v186
	v_cmp_gt_u32_e32 vcc, s52, v69
	v_mov_b32_e32 v67, 0
	v_mov_b32_e32 v68, 0
	s_and_saveexec_b64 s[56:57], vcc
	v_lshl_add_u32 v68, v69, 1, 0
	v_add_u32_e32 v68, 0x12000, v68
	ds_read_u16 v68, v68
	s_or_b64 exec, exec, s[56:57]
	v_add_u32_e32 v69, s73, v187
	v_cmp_gt_u32_e32 vcc, s52, v69
	s_and_saveexec_b64 s[56:57], vcc
	v_lshl_add_u32 v67, v69, 1, 0
	v_add_u32_e32 v67, 0x12000, v67
	ds_read_u16 v67, v67
	s_or_b64 exec, exec, s[56:57]
	s_waitcnt lgkmcnt(2)
	v_add_u32_e32 v71, s73, v188
	v_cmp_gt_u32_e32 vcc, s52, v71
	v_mov_b32_e32 v69, 0
	v_mov_b32_e32 v70, 0
	s_and_saveexec_b64 s[56:57], vcc
	v_lshl_add_u32 v70, v71, 1, 0
	v_add_u32_e32 v70, 0x12000, v70
	ds_read_u16 v70, v70
	s_or_b64 exec, exec, s[56:57]
	v_add_u32_e32 v71, s73, v189
	v_cmp_gt_u32_e32 vcc, s52, v71
	s_and_saveexec_b64 s[56:57], vcc
	v_lshl_add_u32 v69, v71, 1, 0
	v_add_u32_e32 v69, 0x12000, v69
	ds_read_u16 v69, v69
	s_or_b64 exec, exec, s[56:57]
	v_add_u32_e32 v73, s73, v190
	v_cmp_gt_u32_e32 vcc, s52, v73
	v_mov_b32_e32 v71, 0
	v_mov_b32_e32 v72, 0
	s_and_saveexec_b64 s[56:57], vcc
	v_lshl_add_u32 v72, v73, 1, 0
	v_add_u32_e32 v72, 0x12000, v72
	ds_read_u16 v72, v72
	s_or_b64 exec, exec, s[56:57]
	v_add_u32_e32 v73, s73, v191
	v_cmp_gt_u32_e32 vcc, s52, v73
	s_and_saveexec_b64 s[56:57], vcc
	v_lshl_add_u32 v71, v73, 1, 0
	v_add_u32_e32 v71, 0x12000, v71
	ds_read_u16 v71, v71
	s_or_b64 exec, exec, s[56:57]
	v_add_u32_e32 v75, s73, v192
	v_cmp_gt_u32_e32 vcc, s52, v75
	v_mov_b32_e32 v73, 0
	v_mov_b32_e32 v74, 0
	s_and_saveexec_b64 s[56:57], vcc
	v_lshl_add_u32 v74, v75, 1, 0
	v_add_u32_e32 v74, 0x12000, v74
	ds_read_u16 v74, v74
	s_or_b64 exec, exec, s[56:57]
	v_add_u32_e32 v75, s73, v193
	v_cmp_gt_u32_e32 vcc, s52, v75
	s_and_saveexec_b64 s[56:57], vcc
	v_lshl_add_u32 v73, v75, 1, 0
	v_add_u32_e32 v73, 0x12000, v73
	ds_read_u16 v73, v73
	s_or_b64 exec, exec, s[56:57]
	v_add_u32_e32 v77, s73, v194
	v_cmp_gt_u32_e32 vcc, s52, v77
	v_mov_b32_e32 v75, 0
	v_mov_b32_e32 v76, 0
	s_and_saveexec_b64 s[56:57], vcc
	v_lshl_add_u32 v76, v77, 1, 0
	v_add_u32_e32 v76, 0x12000, v76
	ds_read_u16 v76, v76
	s_or_b64 exec, exec, s[56:57]
	v_add_u32_e32 v77, s73, v195
	v_cmp_gt_u32_e32 vcc, s52, v77
	s_and_saveexec_b64 s[56:57], vcc
	v_lshl_add_u32 v75, v77, 1, 0
	v_add_u32_e32 v75, 0x12000, v75
	ds_read_u16 v75, v75
	s_or_b64 exec, exec, s[56:57]
	s_waitcnt lgkmcnt(1)
	v_add_u32_e32 v79, s73, v196
	v_cmp_gt_u32_e32 vcc, s52, v79
	v_mov_b32_e32 v77, 0
	v_mov_b32_e32 v78, 0
	s_and_saveexec_b64 s[56:57], vcc
	v_lshl_add_u32 v78, v79, 1, 0
	v_add_u32_e32 v78, 0x12000, v78
	ds_read_u16 v78, v78
	s_or_b64 exec, exec, s[56:57]
	v_add_u32_e32 v79, s73, v197
	v_cmp_gt_u32_e32 vcc, s52, v79
	s_and_saveexec_b64 s[56:57], vcc
	v_lshl_add_u32 v77, v79, 1, 0
	v_add_u32_e32 v77, 0x12000, v77
	ds_read_u16 v77, v77
	s_or_b64 exec, exec, s[56:57]
	v_add_u32_e32 v81, s73, v198
	v_cmp_gt_u32_e32 vcc, s52, v81
	v_mov_b32_e32 v79, 0
	v_mov_b32_e32 v80, 0
	s_and_saveexec_b64 s[56:57], vcc
	v_lshl_add_u32 v80, v81, 1, 0
	v_add_u32_e32 v80, 0x12000, v80
	ds_read_u16 v80, v80
	s_or_b64 exec, exec, s[56:57]
	v_add_u32_e32 v81, s73, v199
	v_cmp_gt_u32_e32 vcc, s52, v81
	s_and_saveexec_b64 s[56:57], vcc
	v_lshl_add_u32 v79, v81, 1, 0
	v_add_u32_e32 v79, 0x12000, v79
	ds_read_u16 v79, v79
	s_or_b64 exec, exec, s[56:57]
	v_add_u32_e32 v83, s73, v200
	v_cmp_gt_u32_e32 vcc, s52, v83
	v_mov_b32_e32 v81, 0
	v_mov_b32_e32 v82, 0
	s_and_saveexec_b64 s[56:57], vcc
	v_lshl_add_u32 v82, v83, 1, 0
	v_add_u32_e32 v82, 0x12000, v82
	ds_read_u16 v82, v82
	s_or_b64 exec, exec, s[56:57]
	v_add_u32_e32 v83, s73, v201
	v_cmp_gt_u32_e32 vcc, s52, v83
	s_and_saveexec_b64 s[56:57], vcc
	v_lshl_add_u32 v81, v83, 1, 0
	v_add_u32_e32 v81, 0x12000, v81
	ds_read_u16 v81, v81
	s_or_b64 exec, exec, s[56:57]
	v_add_u32_e32 v84, s73, v202
	v_cmp_gt_u32_e32 vcc, s52, v84
	s_and_b64 s[6:7], s[50:51], vcc
	v_mov_b32_e32 v83, 0
	s_and_saveexec_b64 s[56:57], s[6:7]
	v_lshl_add_u32 v83, v84, 1, 0
	v_add_u32_e32 v83, 0x12000, v83
	ds_read_u16 v83, v83
	s_or_b64 exec, exec, s[56:57]
.Lhy_wjoin:
	s_bitcmp1_b32 s72, 0
	s_cselect_b32 s6, 0x2480, 0
	s_lshl_b32 s7, s6, 1
	s_add_i32 s7, s7, 0
	s_mul_i32 s56, s1, 0x920
	s_add_i32 s7, s7, s56
	v_lshl_add_u32 v84, v109, 1, s7
	v_add_u32_e32 v84, 0x1a000, v84
	s_waitcnt lgkmcnt(0)
	ds_write_b16 v84, v66
	ds_write_b16 v84, v1 offset:128
	ds_write_b16 v84, v68 offset:256
	ds_write_b16 v84, v67 offset:384
	ds_write_b16 v84, v70 offset:512
	ds_write_b16 v84, v69 offset:640
	ds_write_b16 v84, v72 offset:768
	ds_write_b16 v84, v71 offset:896
	ds_write_b16 v84, v74 offset:1024
	ds_write_b16 v84, v73 offset:1152
	ds_write_b16 v84, v76 offset:1280
	ds_write_b16 v84, v75 offset:1408
	ds_write_b16 v84, v78 offset:1536
	ds_write_b16 v84, v77 offset:1664
	ds_write_b16 v84, v80 offset:1792
	ds_write_b16 v84, v79 offset:1920
	ds_write_b16 v84, v82 offset:2048
	ds_write_b16 v84, v81 offset:2176
	s_and_saveexec_b64 s[56:57], s[50:51]
	ds_write_b16 v84, v83 offset:2304
	s_or_b64 exec, exec, s[56:57]
	v_lshl_add_u32 v1, s6, 1, v209
	s_mov_b32 s56, 0
	s_mov_b32 s57, s33
	s_mov_b32 s73, s97
	s_waitcnt lgkmcnt(0)
	s_barrier
	s_branch .LBB0_854
.Lhy_wfast:
	s_waitcnt lgkmcnt(0)
	v_add_u32_e32 v84, s73, v109
	v_lshl_add_u32 v84, v84, 1, 0
	v_add_u32_e32 v84, 0x12000, v84
	ds_read_u16 v66, v84
	ds_read_u16 v1, v84 offset:128
	ds_read_u16 v68, v84 offset:256
	ds_read_u16 v67, v84 offset:384
	ds_read_u16 v70, v84 offset:512
	ds_read_u16 v69, v84 offset:640
	ds_read_u16 v72, v84 offset:768
	ds_read_u16 v71, v84 offset:896
	ds_read_u16 v74, v84 offset:1024
	ds_read_u16 v73, v84 offset:1152
	ds_read_u16 v76, v84 offset:1280
	ds_read_u16 v75, v84 offset:1408
	s_waitcnt lgkmcnt(6)
	ds_read_u16 v78, v84 offset:1536
	ds_read_u16 v77, v84 offset:1664
	ds_read_u16 v80, v84 offset:1792
	ds_read_u16 v79, v84 offset:1920
	ds_read_u16 v82, v84 offset:2048
	ds_read_u16 v81, v84 offset:2176
	v_mov_b32_e32 v83, 0
	s_and_saveexec_b64 s[56:57], s[50:51]
	ds_read_u16 v83, v84 offset:2304
	s_or_b64 exec, exec, s[56:57]
	s_branch .Lhy_wjoin
